# v90 + the 128 queue-first workgroups take their sample-attention item statically (rank among them) instead of pulling it through the queue atomic; the dynamic queue starts at 128
# speedup vs baseline: 1.0046x; 1.0046x over previous
; __device__ __forceinline__ void p_mixer(const Args& a, int l, LAS unsigned char* lds, int tid, int lane, int wave, int bid, int G) {
;     ...
;         if (!prompt_done && (!qfirst || pulled >= 1 || queue_empty)) {
; #pragma unroll 1
;             for (int it = bid; it < N_AP; it += G) { asm volatile("" : "+v"(tid)); lane = tid & 63; attn_prompt_item(a, l, it, lds, tid, lane, wave); }
;             prompt_done = true; continue;
;         }
;         if (queue_empty) break;
;         if (threadIdx.x == 0) slot[0] = __hip_atomic_fetch_add(head, 1u, __ATOMIC_RELAXED, __HIP_MEMORY_SCOPE_AGENT);
;         __syncthreads();
;         const int q = (int)slot[0];
;         __syncthreads();
;         if (q >= N_AS + N_CV) { queue_empty = true; continue; }
;         ++pulled;
;         asm volatile("" : "+v"(tid)); lane = tid & 63;
;         if (q < N_AS) attn_sample_item(a, l, q, lds, tid, lane, wave);
;         else conv_item(a, l, q - N_AS, lane, wave);
.LBB0_445:
	s_and_b64 vcc, exec, s[0:1]
	s_cbranch_vccz .LBB0_440
	s_xor_b64 s[6:7], s[68:69], -1
	s_mov_b64 s[0:1], -1
	v_readfirstlane_b32 s4, v0
	s_andn2_b64 vcc, exec, s[6:7]
	s_cbranch_vccnz .LBB0_534
	s_mov_b64 s[0:1], exec
	v_readlane_b32 s4, v253, 2
	v_readlane_b32 s5, v253, 3
	s_and_b64 s[4:5], s[0:1], s[4:5]
	s_mov_b64 exec, s[4:5]
	s_cbranch_execz .LBB0_451
	s_mov_b64 s[6:7], exec
	v_mbcnt_lo_u32_b32 v0, s6, 0
	v_mbcnt_hi_u32_b32 v0, s7, v0
	v_cmp_eq_u32_e32 vcc, 0, v0
	s_and_saveexec_b64 s[4:5], vcc
	s_cbranch_execz .LBB0_450
	s_bcnt1_i32_b64 s6, s[6:7]
	v_readlane_b32 s2, v255, 15
	v_mov_b32_e32 v1, s6
	v_readlane_b32 s3, v255, 16
	s_cmp_lg_u32 s42, 0x100
	s_cbranch_scc1 .Lq_dyn
	s_cmp_lg_u32 s93, 0
	s_cbranch_scc1 .Lq_dyn128
	s_bitcmp0_b32 s71, 3
	s_cbranch_scc1 .Lq_dyn128
	s_lshr_b32 s6, s71, 4
	s_lshl_b32 s6, s6, 3
	s_and_b32 s7, s71, 7
	s_or_b32 s6, s6, s7
	v_mov_b32_e32 v1, s6
	s_branch .LBB0_450
.Lq_dyn128:
	global_atomic_add v1, v173, v1, s[2:3] sc0
	s_waitcnt vmcnt(0)
	v_add_u32_e32 v1, 0x80, v1
	s_branch .LBB0_450
.Lq_dyn:
	global_atomic_add v1, v173, v1, s[2:3] sc0
